# GEMM K-loop: one static s_setprio 1 for waves 4-7 at phase entry, the 16 per-MFMA-block priority flips removed
# speedup vs baseline: 1.0094x; 1.0092x over previous
.LBB0_1022:
	v_readfirstlane_b32 s101, v135
	s_nop 1
	s_lshr_b32 s101, s101, 6
	s_cmp_ge_u32 s101, 4
	s_mov_b32 s101, 0
	s_cbranch_scc0 .Lprio_done
	s_setprio 1

.LBB0_1032:
	v_add_u32_e32 v0, s85, v217
	ds_read_b128 v[130:133], v0
	ds_read_b128 v[150:153], v0 offset:1024
	ds_read_b128 v[154:157], v0 offset:2048
	ds_read_b128 v[158:161], v0 offset:3072
	s_add_i32 s40, s20, 2
	s_add_u32 s24, s0, 0x80
	s_addc_u32 s21, s1, 0
	s_cmp_eq_u32 s73, s20
	s_cselect_b32 s20, s64, s24
	s_cselect_b32 s21, s65, s21
	s_cselect_b32 s25, s67, s39
	s_cselect_b32 s24, s66, s38
	v_lshl_add_u64 v[194:195], s[0:1], 0, v[146:147]
	s_add_i32 m0, s60, 0xc000
	ds_read_b128 v[162:165], v220
	ds_read_b128 v[166:169], v220 offset:1024
	ds_read_b128 v[170:173], v220 offset:2048
	ds_read_b128 v[174:177], v220 offset:3072
	ds_read_b128 v[178:181], v220 offset:4096
	ds_read_b128 v[182:185], v220 offset:5120
	ds_read_b128 v[186:189], v220 offset:6144
	ds_read_b128 v[190:193], v220 offset:7168
	global_load_lds_dwordx4 v[194:195], off
	v_lshl_add_u64 v[194:195], s[0:1], 0, v[148:149]
	s_add_i32 m0, s60, 0xe000
	s_nop 0
	global_load_lds_dwordx4 v[194:195], off
	s_waitcnt lgkmcnt(8)
	s_barrier
	s_waitcnt lgkmcnt(0)
	s_waitcnt lgkmcnt(0)
	v_mfma_f32_16x16x32_bf16 v[126:129], v[130:133], v[162:165], v[126:129]
	v_mfma_f32_16x16x32_bf16 v[122:125], v[154:157], v[162:165], v[122:125]
	v_mfma_f32_16x16x32_bf16 v[118:121], v[130:133], v[170:173], v[118:121]
	v_mfma_f32_16x16x32_bf16 v[114:117], v[154:157], v[170:173], v[114:117]
	v_mfma_f32_16x16x32_bf16 v[110:113], v[130:133], v[178:181], v[110:113]
	v_mfma_f32_16x16x32_bf16 v[106:109], v[154:157], v[178:181], v[106:109]
	v_mfma_f32_16x16x32_bf16 v[102:105], v[130:133], v[186:189], v[102:105]
	v_mfma_f32_16x16x32_bf16 v[98:101], v[154:157], v[186:189], v[98:101]
	v_mfma_f32_16x16x32_bf16 v[126:129], v[150:153], v[166:169], v[126:129]
	v_mfma_f32_16x16x32_bf16 v[122:125], v[158:161], v[166:169], v[122:125]
	v_mfma_f32_16x16x32_bf16 v[118:121], v[150:153], v[174:177], v[118:121]
	v_mfma_f32_16x16x32_bf16 v[114:117], v[158:161], v[174:177], v[114:117]
	v_mfma_f32_16x16x32_bf16 v[110:113], v[150:153], v[182:185], v[110:113]
	v_mfma_f32_16x16x32_bf16 v[106:109], v[158:161], v[182:185], v[106:109]
	v_mfma_f32_16x16x32_bf16 v[102:105], v[150:153], v[190:193], v[102:105]
	v_mfma_f32_16x16x32_bf16 v[98:101], v[158:161], v[190:193], v[98:101]
	s_barrier
	s_add_i32 s41, s85, s63
	v_add_u32_e32 v0, s96, v217
	v_lshl_add_u64 v[236:237], s[24:25], 0, v[138:139]
	s_mov_b32 m0, s41
	ds_read_b128 v[194:197], v0
	ds_read_b128 v[224:227], v0 offset:1024
	ds_read_b128 v[228:231], v0 offset:2048
	ds_read_b128 v[232:235], v0 offset:3072
	global_load_lds_dwordx4 v[236:237], off
	v_lshl_add_u64 v[238:239], s[24:25], 0, v[140:141]
	s_add_i32 m0, s41, 0x2000
	s_nop 0
	global_load_lds_dwordx4 v[238:239], off
	s_barrier
	s_waitcnt lgkmcnt(0)
	s_waitcnt lgkmcnt(0)
	v_mfma_f32_16x16x32_bf16 v[62:65], v[194:197], v[162:165], v[62:65]
	v_mfma_f32_16x16x32_bf16 v[58:61], v[228:231], v[162:165], v[58:61]
	v_mfma_f32_16x16x32_bf16 v[54:57], v[194:197], v[170:173], v[54:57]
	v_mfma_f32_16x16x32_bf16 v[50:53], v[228:231], v[170:173], v[50:53]
	v_mfma_f32_16x16x32_bf16 v[46:49], v[194:197], v[178:181], v[46:49]
	v_mfma_f32_16x16x32_bf16 v[42:45], v[228:231], v[178:181], v[42:45]
	v_mfma_f32_16x16x32_bf16 v[38:41], v[194:197], v[186:189], v[38:41]
	v_mfma_f32_16x16x32_bf16 v[34:37], v[228:231], v[186:189], v[34:37]
	v_mfma_f32_16x16x32_bf16 v[62:65], v[224:227], v[166:169], v[62:65]
	v_mfma_f32_16x16x32_bf16 v[58:61], v[232:235], v[166:169], v[58:61]
	v_mfma_f32_16x16x32_bf16 v[54:57], v[224:227], v[174:177], v[54:57]
	v_mfma_f32_16x16x32_bf16 v[50:53], v[232:235], v[174:177], v[50:53]
	v_mfma_f32_16x16x32_bf16 v[46:49], v[224:227], v[182:185], v[46:49]
	v_mfma_f32_16x16x32_bf16 v[42:45], v[232:235], v[182:185], v[42:45]
	v_mfma_f32_16x16x32_bf16 v[38:41], v[224:227], v[190:193], v[38:41]
	v_mfma_f32_16x16x32_bf16 v[34:37], v[232:235], v[190:193], v[34:37]
	s_mov_b32 m0, s60
	v_lshl_add_u64 v[240:241], s[20:21], 0, v[138:139]
	s_barrier
	ds_read_b128 v[162:165], v220 offset:16384
	ds_read_b128 v[166:169], v220 offset:17408
	ds_read_b128 v[170:173], v220 offset:18432
	ds_read_b128 v[174:177], v220 offset:19456
	ds_read_b128 v[178:181], v220 offset:20480
	ds_read_b128 v[182:185], v220 offset:21504
	ds_read_b128 v[186:189], v220 offset:22528
	ds_read_b128 v[190:193], v220 offset:23552
	global_load_lds_dwordx4 v[240:241], off
	v_lshl_add_u64 v[242:243], s[20:21], 0, v[140:141]
	s_mov_b32 m0, s61
	s_nop 0
	global_load_lds_dwordx4 v[242:243], off
	s_barrier
	s_waitcnt lgkmcnt(0)
	s_waitcnt lgkmcnt(0)
	v_mfma_f32_16x16x32_bf16 v[94:97], v[130:133], v[162:165], v[94:97]
	v_mfma_f32_16x16x32_bf16 v[90:93], v[154:157], v[162:165], v[90:93]
	v_mfma_f32_16x16x32_bf16 v[86:89], v[130:133], v[170:173], v[86:89]
	v_mfma_f32_16x16x32_bf16 v[82:85], v[154:157], v[170:173], v[82:85]
	v_mfma_f32_16x16x32_bf16 v[78:81], v[130:133], v[178:181], v[78:81]
	v_mfma_f32_16x16x32_bf16 v[74:77], v[154:157], v[178:181], v[74:77]
	v_mfma_f32_16x16x32_bf16 v[70:73], v[130:133], v[186:189], v[70:73]
	v_mfma_f32_16x16x32_bf16 v[66:69], v[154:157], v[186:189], v[66:69]
	v_mfma_f32_16x16x32_bf16 v[94:97], v[150:153], v[166:169], v[94:97]
	v_mfma_f32_16x16x32_bf16 v[90:93], v[158:161], v[166:169], v[90:93]
	v_mfma_f32_16x16x32_bf16 v[86:89], v[150:153], v[174:177], v[86:89]
	v_mfma_f32_16x16x32_bf16 v[82:85], v[158:161], v[174:177], v[82:85]
	v_mfma_f32_16x16x32_bf16 v[78:81], v[150:153], v[182:185], v[78:81]
	v_mfma_f32_16x16x32_bf16 v[74:77], v[158:161], v[182:185], v[74:77]
	v_mfma_f32_16x16x32_bf16 v[70:73], v[150:153], v[190:193], v[70:73]
	v_mfma_f32_16x16x32_bf16 v[66:69], v[158:161], v[190:193], v[66:69]
	s_barrier
	s_add_u32 s24, s24, s74
	s_addc_u32 s25, s25, 0
	s_add_i32 s41, s96, s63
	v_lshl_add_u64 v[244:245], s[24:25], 0, v[138:139]
	s_mov_b32 m0, s41
	v_lshl_add_u64 v[246:247], s[24:25], 0, v[140:141]
	global_load_lds_dwordx4 v[244:245], off
	s_add_i32 m0, s41, 0x2000
	s_nop 0
	global_load_lds_dwordx4 v[246:247], off
	s_waitcnt vmcnt(6)
	s_barrier
	v_mfma_f32_16x16x32_bf16 v[30:33], v[194:197], v[162:165], v[30:33]
	v_mfma_f32_16x16x32_bf16 v[26:29], v[228:231], v[162:165], v[26:29]
	v_mfma_f32_16x16x32_bf16 v[22:25], v[194:197], v[170:173], v[22:25]
	v_mfma_f32_16x16x32_bf16 v[18:21], v[228:231], v[170:173], v[18:21]
	v_mfma_f32_16x16x32_bf16 v[14:17], v[194:197], v[178:181], v[14:17]
	v_mfma_f32_16x16x32_bf16 v[10:13], v[228:231], v[178:181], v[10:13]
	v_mfma_f32_16x16x32_bf16 v[6:9], v[194:197], v[186:189], v[6:9]
	v_mfma_f32_16x16x32_bf16 v[2:5], v[228:231], v[186:189], v[2:5]
	v_mfma_f32_16x16x32_bf16 v[30:33], v[224:227], v[166:169], v[30:33]
	v_mfma_f32_16x16x32_bf16 v[26:29], v[232:235], v[166:169], v[26:29]
	v_mfma_f32_16x16x32_bf16 v[22:25], v[224:227], v[174:177], v[22:25]
	v_mfma_f32_16x16x32_bf16 v[18:21], v[232:235], v[174:177], v[18:21]
	v_mfma_f32_16x16x32_bf16 v[14:17], v[224:227], v[182:185], v[14:17]
	v_mfma_f32_16x16x32_bf16 v[10:13], v[232:235], v[182:185], v[10:13]
	v_mfma_f32_16x16x32_bf16 v[6:9], v[224:227], v[190:193], v[6:9]
	v_mfma_f32_16x16x32_bf16 v[2:5], v[232:235], v[190:193], v[2:5]
	s_mov_b32 s24, 0x18000
	s_addk_i32 s24, 0x50
	v_add_u32_e32 v0, s24, v217
	s_barrier
	ds_read_b128 v[130:133], v0
	ds_read_b128 v[150:153], v0 offset:1024
	ds_read_b128 v[154:157], v0 offset:2048
	ds_read_b128 v[158:161], v0 offset:3072
	s_add_u32 s20, s20, s74
	s_addc_u32 s21, s21, 0
	s_mov_b32 m0, s58
	v_lshl_add_u64 v[194:195], s[20:21], 0, v[138:139]
	ds_read_b128 v[162:165], v220 offset:32768
	ds_read_b128 v[166:169], v220 offset:33792
	ds_read_b128 v[170:173], v220 offset:34816
	ds_read_b128 v[174:177], v220 offset:35840
	ds_read_b128 v[178:181], v220 offset:36864
	ds_read_b128 v[182:185], v220 offset:37888
	ds_read_b128 v[186:189], v220 offset:38912
	ds_read_b128 v[190:193], v220 offset:39936
	global_load_lds_dwordx4 v[194:195], off
	v_lshl_add_u64 v[194:195], s[20:21], 0, v[140:141]
	s_mov_b32 m0, s59
	s_nop 0
	global_load_lds_dwordx4 v[194:195], off
	s_waitcnt lgkmcnt(8)
	s_barrier
	s_waitcnt lgkmcnt(0)
	s_waitcnt lgkmcnt(0)
	v_mfma_f32_16x16x32_bf16 v[126:129], v[130:133], v[162:165], v[126:129]
	v_mfma_f32_16x16x32_bf16 v[122:125], v[154:157], v[162:165], v[122:125]
	v_mfma_f32_16x16x32_bf16 v[118:121], v[130:133], v[170:173], v[118:121]
	v_mfma_f32_16x16x32_bf16 v[114:117], v[154:157], v[170:173], v[114:117]
	v_mfma_f32_16x16x32_bf16 v[110:113], v[130:133], v[178:181], v[110:113]
	v_mfma_f32_16x16x32_bf16 v[106:109], v[154:157], v[178:181], v[106:109]
	v_mfma_f32_16x16x32_bf16 v[102:105], v[130:133], v[186:189], v[102:105]
	v_mfma_f32_16x16x32_bf16 v[98:101], v[154:157], v[186:189], v[98:101]
	v_mfma_f32_16x16x32_bf16 v[126:129], v[150:153], v[166:169], v[126:129]
	v_mfma_f32_16x16x32_bf16 v[122:125], v[158:161], v[166:169], v[122:125]
	v_mfma_f32_16x16x32_bf16 v[118:121], v[150:153], v[174:177], v[118:121]
	v_mfma_f32_16x16x32_bf16 v[114:117], v[158:161], v[174:177], v[114:117]
	v_mfma_f32_16x16x32_bf16 v[110:113], v[150:153], v[182:185], v[110:113]
	v_mfma_f32_16x16x32_bf16 v[106:109], v[158:161], v[182:185], v[106:109]
	v_mfma_f32_16x16x32_bf16 v[102:105], v[150:153], v[190:193], v[102:105]
	v_mfma_f32_16x16x32_bf16 v[98:101], v[158:161], v[190:193], v[98:101]
	s_barrier
	s_add_i32 s20, s24, s63
	v_add_u32_e32 v0, s97, v217
	v_lshl_add_u64 v[236:237], v[236:237], 0, s[82:83]
	s_mov_b32 m0, s20
	ds_read_b128 v[194:197], v0
	ds_read_b128 v[224:227], v0 offset:1024
	ds_read_b128 v[228:231], v0 offset:2048
	ds_read_b128 v[232:235], v0 offset:3072
	global_load_lds_dwordx4 v[236:237], off
	v_lshl_add_u64 v[236:237], v[238:239], 0, s[82:83]
	s_add_i32 m0, s20, 0x2000
	s_nop 0
	global_load_lds_dwordx4 v[236:237], off
	s_barrier
	s_waitcnt lgkmcnt(0)
	s_waitcnt lgkmcnt(0)
	v_mfma_f32_16x16x32_bf16 v[62:65], v[194:197], v[162:165], v[62:65]
	v_mfma_f32_16x16x32_bf16 v[58:61], v[228:231], v[162:165], v[58:61]
	v_mfma_f32_16x16x32_bf16 v[54:57], v[194:197], v[170:173], v[54:57]
	v_mfma_f32_16x16x32_bf16 v[50:53], v[228:231], v[170:173], v[50:53]
	v_mfma_f32_16x16x32_bf16 v[46:49], v[194:197], v[178:181], v[46:49]
	v_mfma_f32_16x16x32_bf16 v[42:45], v[228:231], v[178:181], v[42:45]
	v_mfma_f32_16x16x32_bf16 v[38:41], v[194:197], v[186:189], v[38:41]
	v_mfma_f32_16x16x32_bf16 v[34:37], v[228:231], v[186:189], v[34:37]
	v_mfma_f32_16x16x32_bf16 v[62:65], v[224:227], v[166:169], v[62:65]
	v_mfma_f32_16x16x32_bf16 v[58:61], v[232:235], v[166:169], v[58:61]
	v_mfma_f32_16x16x32_bf16 v[54:57], v[224:227], v[174:177], v[54:57]
	v_mfma_f32_16x16x32_bf16 v[50:53], v[232:235], v[174:177], v[50:53]
	v_mfma_f32_16x16x32_bf16 v[46:49], v[224:227], v[182:185], v[46:49]
	v_mfma_f32_16x16x32_bf16 v[42:45], v[232:235], v[182:185], v[42:45]
	v_mfma_f32_16x16x32_bf16 v[38:41], v[224:227], v[190:193], v[38:41]
	v_mfma_f32_16x16x32_bf16 v[34:37], v[232:235], v[190:193], v[34:37]
	s_mov_b32 m0, s78
	v_lshl_add_u64 v[236:237], v[240:241], 0, s[82:83]
	s_barrier
	ds_read_b128 v[162:165], v220 offset:49152
	ds_read_b128 v[166:169], v220 offset:50176
	ds_read_b128 v[170:173], v220 offset:51200
	ds_read_b128 v[174:177], v220 offset:52224
	ds_read_b128 v[178:181], v220 offset:53248
	ds_read_b128 v[182:185], v220 offset:54272
	ds_read_b128 v[186:189], v220 offset:55296
	ds_read_b128 v[190:193], v220 offset:56320
	global_load_lds_dwordx4 v[236:237], off
	v_lshl_add_u64 v[236:237], v[242:243], 0, s[82:83]
	s_mov_b32 m0, s23
	s_nop 0
	global_load_lds_dwordx4 v[236:237], off
	s_barrier
	s_waitcnt lgkmcnt(0)
	s_waitcnt lgkmcnt(0)
	v_mfma_f32_16x16x32_bf16 v[94:97], v[130:133], v[162:165], v[94:97]
	v_mfma_f32_16x16x32_bf16 v[90:93], v[154:157], v[162:165], v[90:93]
	v_mfma_f32_16x16x32_bf16 v[86:89], v[130:133], v[170:173], v[86:89]
	v_mfma_f32_16x16x32_bf16 v[82:85], v[154:157], v[170:173], v[82:85]
	v_mfma_f32_16x16x32_bf16 v[78:81], v[130:133], v[178:181], v[78:81]
	v_mfma_f32_16x16x32_bf16 v[74:77], v[154:157], v[178:181], v[74:77]
	v_mfma_f32_16x16x32_bf16 v[70:73], v[130:133], v[186:189], v[70:73]
	v_mfma_f32_16x16x32_bf16 v[66:69], v[154:157], v[186:189], v[66:69]
	v_mfma_f32_16x16x32_bf16 v[94:97], v[150:153], v[166:169], v[94:97]
	v_mfma_f32_16x16x32_bf16 v[90:93], v[158:161], v[166:169], v[90:93]
	v_mfma_f32_16x16x32_bf16 v[86:89], v[150:153], v[174:177], v[86:89]
	v_mfma_f32_16x16x32_bf16 v[82:85], v[158:161], v[174:177], v[82:85]
	v_mfma_f32_16x16x32_bf16 v[78:81], v[150:153], v[182:185], v[78:81]
	v_mfma_f32_16x16x32_bf16 v[74:77], v[158:161], v[182:185], v[74:77]
	v_mfma_f32_16x16x32_bf16 v[70:73], v[150:153], v[190:193], v[70:73]
	v_mfma_f32_16x16x32_bf16 v[66:69], v[158:161], v[190:193], v[66:69]
	s_barrier
	s_add_i32 s20, s97, s63
	v_lshl_add_u64 v[130:131], v[244:245], 0, s[82:83]
	s_mov_b32 m0, s20
	s_nop 0
	global_load_lds_dwordx4 v[130:131], off
	v_lshl_add_u64 v[130:131], v[246:247], 0, s[82:83]
	s_add_i32 m0, s20, 0x2000
	s_nop 0
	global_load_lds_dwordx4 v[130:131], off
	s_waitcnt vmcnt(6)
	s_barrier
	v_mfma_f32_16x16x32_bf16 v[30:33], v[194:197], v[162:165], v[30:33]
	v_mfma_f32_16x16x32_bf16 v[26:29], v[228:231], v[162:165], v[26:29]
	v_mfma_f32_16x16x32_bf16 v[22:25], v[194:197], v[170:173], v[22:25]
	v_mfma_f32_16x16x32_bf16 v[18:21], v[228:231], v[170:173], v[18:21]
	v_mfma_f32_16x16x32_bf16 v[14:17], v[194:197], v[178:181], v[14:17]
	v_mfma_f32_16x16x32_bf16 v[10:13], v[228:231], v[178:181], v[10:13]
	v_mfma_f32_16x16x32_bf16 v[6:9], v[194:197], v[186:189], v[6:9]
	v_mfma_f32_16x16x32_bf16 v[2:5], v[228:231], v[186:189], v[2:5]
	v_mfma_f32_16x16x32_bf16 v[30:33], v[224:227], v[166:169], v[30:33]
	v_mfma_f32_16x16x32_bf16 v[26:29], v[232:235], v[166:169], v[26:29]
	v_mfma_f32_16x16x32_bf16 v[22:25], v[224:227], v[174:177], v[22:25]
	v_mfma_f32_16x16x32_bf16 v[18:21], v[232:235], v[174:177], v[18:21]
	v_mfma_f32_16x16x32_bf16 v[14:17], v[224:227], v[182:185], v[14:17]
	v_mfma_f32_16x16x32_bf16 v[10:13], v[232:235], v[182:185], v[10:13]
	v_mfma_f32_16x16x32_bf16 v[6:9], v[224:227], v[190:193], v[6:9]
	v_mfma_f32_16x16x32_bf16 v[2:5], v[232:235], v[190:193], v[2:5]
	s_add_u32 s0, s0, 0x100
	s_addc_u32 s1, s1, 0
	s_add_u32 s38, s38, 0x100
	s_addc_u32 s39, s39, 0
	s_cmp_ge_u32 s40, s34
	s_mov_b32 s20, s40
	s_barrier
	s_cbranch_scc0 .LBB0_1032
	s_lshl_b32 s24, s26, 8
	s_cmp_lt_i32 s56, 1
	s_mov_b64 s[0:1], -1
	s_cbranch_scc1 .LBB0_1279
	s_cmp_lg_u32 s56, 1
	s_cbranch_scc0 .LBB0_1276
	s_add_i32 s0, s24, 0xfffff000
	s_lshr_b32 s0, s0, 12
	s_add_i32 s0, s0, 1
	s_cmp_gt_i32 s26, 15
	v_readlane_b32 s4, v249, 47
	s_cselect_b32 s0, s0, 0
	v_readlane_b32 s5, v248, 2
	v_readlane_b32 s6, v248, 3
	s_mul_i32 s1, s4, 3
	s_add_i32 s0, s0, s1
	s_mulk_i32 s0, 0x1800
	s_ashr_i32 s1, s0, 31
	s_lshl_b64 s[0:1], s[0:1], 2
	s_add_u32 s0, s5, s0
	s_addc_u32 s1, s6, s1
	v_lshl_or_b32 v0, s42, 8, v218
	v_lshlrev_b32_e32 v0, 2, v0
	global_load_dwordx4 v[130:133], v0, s[0:1] offset:0
	s_add_u32 s8, s94, 0x139d6000
	s_addc_u32 s9, s95, 0
	s_add_u32 s10, s94, 0x1e40000
	s_addc_u32 s11, s95, 0
	s_cmp_eq_u32 s56, 3
	s_cbranch_scc1 .Lepi_w1
	s_mov_b64 s[12:13], s[8:9]
	s_mov_b64 s[14:15], s[10:11]
	s_cmp_lg_u32 s4, 0
	s_cbranch_scc1 .Lepi_bd
	v_readlane_b32 s14, v250, 43
	v_readlane_b32 s15, v250, 44
	s_cmp_lt_i32 s24, 0x1000
	s_cbranch_scc1 .Lepi_bd
	v_readlane_b32 s14, v250, 45
	v_readlane_b32 s15, v250, 46
	s_nop 1
	s_sub_u32 s14, s14, 0x1000000
	s_subb_u32 s15, s15, 0
	s_branch .Lepi_bd

.LBB0_1856:
	s_setprio 0
	s_waitcnt vmcnt(0)
	v_readlane_b32 s0, v249, 63
	s_cmpk_gt_u32 s0, 0xff
	s_cbranch_scc1 .LBB0_1858
	s_barrier
